# Static priority raise for waves 4-7 also across the attention unit loops (both even layers)
# baseline (speedup 1.0000x reference)
.LBB0_229:
	v_lshlrev_b32_e32 v225, 2, v206
	v_add_u32_e32 v225, 0x1b000, v225
	ds_write_b32 v225, v254
	v_readfirstlane_b32 s101, v206
	s_nop 3
	s_lshr_b32 s101, s101, 8
	s_cmp_eq_u32 s101, 1
	s_cbranch_scc0 .Lprio_attn_0
	s_setprio 1
.Lprio_attn_0:
	s_nop 0
	s_mov_b32 s26, 0xffff0000
	s_mov_b32 s9, 0
	v_mov_b32_e32 v1, 0
	s_mov_b64 s[10:11], 0x12000000
	s_mov_b64 s[12:13], 0x14000000
	s_mov_b64 s[14:15], 0x12010000
	s_mov_b64 s[16:17], 0x10000000
	s_brev_b32 s51, 8
	s_mov_b64 s[18:19], 0x12020000
	s_mov_b64 s[20:21], 0x30000
	s_mov_b64 s[22:23], 0x10000
	s_mov_b64 s[24:25], 0x50000
	s_mov_b32 s27, -1
	s_mov_b32 s52, 0x41000000
	s_mov_b64 s[28:29], 0x20000
	s_mov_b64 s[30:31], 0x40000
	s_mov_b64 s[34:35], 0x1c000000
	v_mov_b32_e32 v207, 0xff800000
	s_branch .LBB0_231

.Lattn_rest_0:
	s_setprio 0
	s_nop 0
	v_lshlrev_b32_e32 v225, 2, v206
	v_add_u32_e32 v225, 0x1b000, v225
	ds_read_b32 v254, v225
	s_waitcnt lgkmcnt(0)

.Lprio_attn_1:
	s_nop 0
	s_mov_b32 s26, 0xffff0000
	s_mov_b32 s9, 0
	v_mov_b32_e32 v1, 0
	s_mov_b64 s[10:11], 0x12000000
	s_mov_b64 s[12:13], 0x14000000
	s_mov_b64 s[14:15], 0x12010000
	s_mov_b64 s[16:17], 0x10000000
	s_brev_b32 s51, 8
	s_mov_b64 s[18:19], 0x12020000
	s_mov_b64 s[20:21], 0x30000
	s_mov_b64 s[22:23], 0x10000
	s_mov_b64 s[24:25], 0x50000
	s_mov_b32 s27, -1
	s_mov_b32 s52, 0x41000000
	s_mov_b64 s[28:29], 0x20000
	s_mov_b64 s[30:31], 0x40000
	s_mov_b64 s[34:35], 0x1c000000
	v_mov_b32_e32 v208, 0xff800000
	s_branch .LBB0_1711
